# phase 1 w_in conversion: contiguous tile ranges weighted 17:21 against the blocks that carry a 17th rmsnorm (context) row
# baseline (speedup 1.0000x reference)
; DI unsigned pk2(float lo, float hi) { f32x2 v = {lo, hi}; bfv2 r = __builtin_convertvector(v, bfv2); return __builtin_bit_cast(unsigned, r); }
; DI void wconv(const float* __restrict__ src, int ld, int K, int col0, int ncols, bf16_t* __restrict__ dst, int dstld, int drow0, int mode, int bid, int nb) {
;   float* t = (float*)g_smem;
;   const int tid = threadIdx.x;
;   if ((ncols & 63) == 0) {
;     const int ntn = ncols / 64, ntk = K / 64, nt = ntn * ntk;
;     for (int it = bid; it < nt; it += nb) {
;       const int tn = it % ntn, tk = it / ntn;
; #pragma unroll
;       for (int q = 0; q < 8; ++q) { int e = tid + 512 * q; int r = e >> 6, c = e & 63; t[r * 65 + c] = src[(size_t)(tk * 64 + r) * ld + col0 + tn * 64 + c]; }
;       __syncthreads();
;       { int n = tid >> 3, kk = (tid & 7) * 8; int cs = tn * 64 + n;
;         int drow = mode == 0 ? drow0 + cs : ((cs >> 7) * 256 + drow0 + (cs & 127));
;         u32x4 v; v.x = pk2(t[(kk) * 65 + n], t[(kk + 1) * 65 + n]); v.y = pk2(t[(kk + 2) * 65 + n], t[(kk + 3) * 65 + n]);
;         v.z = pk2(t[(kk + 4) * 65 + n], t[(kk + 5) * 65 + n]); v.w = pk2(t[(kk + 6) * 65 + n], t[(kk + 7) * 65 + n]);
;         *(u32x4*)(dst + (size_t)drow * dstld + tk * 64 + kk) = v; }
;       __syncthreads();
;     }
;     return;
;   }
;   const int ntn = ncols / 32, ntk = K / 64, nt = ntn * ntk;
;   for (int it = bid; it < nt; it += nb) {
;     const int tn = it % ntn, tk = it / ntn;
.Lwc1_go:
	s_nop 1
	s_add_u32 s10, s10, s15
	s_addc_u32 s11, s11, 0
	v_mul_lo_u32 v8, v2, s12
	v_lshlrev_b32_e32 v8, 2, v8
	v_lshl_add_u32 v8, v3, 4, v8
	s_lshl_b32 s29, s12, 7
	v_add_u32_e32 v13, s29, v8
	v_mul_lo_u32 v9, v4, s18
	v_lshlrev_b32_e32 v9, 1, v9
	v_lshl_add_u32 v9, v5, 4, v9
	v_cmp_gt_u32_e32 vcc, s21, v4
	s_nop 1
	v_cndmask_b32_e64 v12, 0, 1, vcc
	s_mul_i32 s14, s14, s13
	s_cmp_eq_u32 s88, 0x100
	s_cbranch_scc0 .Lwc1_strided
	s_cmp_lt_u32 s2, 64
	s_cbranch_scc0 .Lwc1_cwbig
	s_mul_i32 s15, s2, 17
	s_add_u32 s21, s15, 17
	s_branch .Lwc1_cwd
.Lwc1_cwbig:
	s_sub_u32 s15, s2, 64
	s_mul_i32 s15, s15, 21
	s_add_u32 s15, s15, 0x440
	s_add_u32 s21, s15, 21
.Lwc1_cwd:
	s_mul_i32 s6, s14, s15
	s_lshr_b32 s6, s6, 7
	s_mul_hi_u32 s6, s6, 0xcccccccd
	s_lshr_b32 s6, s6, 5
	s_mul_i32 s29, s14, s21
	s_lshr_b32 s29, s29, 7
	s_mul_hi_u32 s29, s29, 0xcccccccd
	s_lshr_b32 s29, s29, 5
	s_sub_u32 s4, s29, s6
	s_cmp_eq_u32 s4, 0
	s_cbranch_scc1 .Lwc1_jobdone
	s_mov_b32 s7, 0
